# SSM pass 2: skip conservative vmcnt waits on middle chunks so the next-chunk prefetch stays in flight
# baseline (speedup 1.0000x reference)
; #define SSM_SCAN_STEP(D, SQ) { _Pragma("unroll") for (int r = 0; r < 4; ++r) { \
;                     const float sr = dppf<DPP_SHR(D)>(Er[r]), si = dppf<DPP_SHR(D)>(Ei[r]); \
;                     Er[r] += mr[r] * sr - mi[r] * si; Ei[r] += mr[r] * si + mi[r] * sr; \
;                     if (SQ) { const float nr = mr[r] * mr[r] - mi[r] * mi[r], ni = 2.f * mr[r] * mi[r]; mr[r] = nr; mi[r] = ni; } } }
; template <bool PASS2>
; __device__ __forceinline__ void ssm_phase(const Params& p, const Frame& F0) {
;     ...
;             for (int i = 0; i < 4; ++i) {
;                 __builtin_amdgcn_sched_barrier(0);
;                 f32x4 Er = (f32x4){0.f, 0.f, 0.f, 0.f}, Ei = Er;
; #pragma unroll
;                 for (int ks = 0; ks < 4; ++ks) { Er = __builtin_amdgcn_mfma_f32_16x16x32_bf16(frag[(i * 4 + ks) * 64], uf[ks], Er, 0, 0, 0);
;                                                  Ei = __builtin_amdgcn_mfma_f32_16x16x32_bf16(frag[((i + 4) * 4 + ks) * 64], uf[ks], Ei, 0, 0, 0); }
;                 const f32x4 ma = m1t[8 * i], mb = m1t[8 * i + 1];
;                 float mr[4] = {ma[0], ma[2], mb[0], mb[2]}, mi[4] = {ma[1], ma[3], mb[1], mb[3]};
;                 float hr[4], hi[4];
; #pragma unroll
;                 for (int r = 0; r < 4; ++r) { hr[r] = dppf<DPP_ROR(1)>(xs[i][r]); hi[r] = dppf<DPP_ROR(1)>(xs[i + 4][r]);
;                     if (j == 0) { Er[r] += mr[r] * hr[r] - mi[r] * hi[r]; Ei[r] += mr[r] * hi[r] + mi[r] * hr[r]; } }
;     ...
;                 SSM_SCAN_STEP(1, 1) SSM_SCAN_STEP(2, 1) SSM_SCAN_STEP(4, 1) SSM_SCAN_STEP(8, 0)
.LBB0_646:
	s_or_b64 s[24:25], s[26:27], s[8:9]
	s_and_b64 s[26:27], exec, s[26:27]
	s_cselect_b32 s26, s30, s43
	ds_read_b128 v[68:71], v105
	ds_read_b128 v[72:75], v105 offset:1024
	ds_read_b128 v[76:79], v105 offset:16384
	ds_read_b128 v[80:83], v105 offset:17408
	s_and_b32 s98, s3, 0x180
	s_cbranch_scc1 .Lssmw_0
	s_waitcnt vmcnt(7)
.Lssmw_0:
	v_mov_b32_dpp v3, v36 row_ror:1 row_mask:0xf bank_mask:0xf bound_ctrl:1
	s_and_b32 s98, s3, 0x180
	s_cbranch_scc1 .Lssmw_1
	s_waitcnt vmcnt(5)
.Lssmw_1:
	v_mov_b32_dpp v2, v40 row_ror:1 row_mask:0xf bank_mask:0xf bound_ctrl:1
	s_waitcnt lgkmcnt(3)
	v_mfma_f32_16x16x32_bf16 v[68:71], v[68:71], v[56:59], 0
	s_waitcnt lgkmcnt(1)
	v_mfma_f32_16x16x32_bf16 v[76:79], v[76:79], v[56:59], 0
	v_mfma_f32_16x16x32_bf16 v[68:71], v[72:75], v[52:55], v[68:71]
	ds_read_b128 v[72:75], v105 offset:2048
	s_waitcnt lgkmcnt(1)
	v_mfma_f32_16x16x32_bf16 v[76:79], v[80:83], v[52:55], v[76:79]
	ds_read_b128 v[80:83], v105 offset:18432
	s_and_b32 s98, s3, 0x180
	s_cbranch_scc1 .Lssmw_2
	s_waitcnt vmcnt(0)
.Lssmw_2:
	ds_read_b128 v[84:87], v105 offset:3072
	ds_read_b128 v[88:91], v105 offset:19456
	s_waitcnt lgkmcnt(2)
	v_mfma_f32_16x16x32_bf16 v[76:79], v[80:83], v[64:67], v[76:79]
	v_mov_b32_dpp v83, v38 row_ror:1 row_mask:0xf bank_mask:0xf bound_ctrl:1
	v_mov_b32_dpp v82, v42 row_ror:1 row_mask:0xf bank_mask:0xf bound_ctrl:1
	v_mfma_f32_16x16x32_bf16 v[68:71], v[72:75], v[64:67], v[68:71]
	ds_read_b128 v[72:75], v198
	ds_read_b128 v[204:207], v198 offset:16
	s_waitcnt lgkmcnt(1)
	v_pk_mul_f32 v[80:81], v[72:73], v[2:3] op_sel:[0,1] op_sel_hi:[1,0]
	v_mfma_f32_16x16x32_bf16 v[76:79], v[88:91], v[60:63], v[76:79]
	v_sub_f32_e32 v1, v80, v81
	v_pk_mul_f32 v[80:81], v[72:73], v[2:3]
	v_mov_b32_e32 v90, v73
	v_mfma_f32_16x16x32_bf16 v[68:71], v[84:87], v[60:63], v[68:71]
	v_add_f32_e32 v36, v81, v80
	v_mov_b32_dpp v81, v37 row_ror:1 row_mask:0xf bank_mask:0xf bound_ctrl:1
	v_mov_b32_dpp v80, v41 row_ror:1 row_mask:0xf bank_mask:0xf bound_ctrl:1
	s_nop 0
	v_add_f32_e32 v40, v76, v36
	v_pk_mul_f32 v[36:37], v[74:75], v[80:81] op_sel:[0,1] op_sel_hi:[1,0]
	v_mov_b32_dpp v85, v39 row_ror:1 row_mask:0xf bank_mask:0xf bound_ctrl:1
	v_sub_f32_e32 v36, v36, v37
	v_add_f32_e32 v41, v36, v69
	v_pk_mul_f32 v[36:37], v[74:75], v[80:81]
	v_mov_b32_dpp v84, v43 row_ror:1 row_mask:0xf bank_mask:0xf bound_ctrl:1
	v_add_f32_e32 v36, v37, v36
	v_add_f32_e32 v86, v36, v77
	s_waitcnt lgkmcnt(0)
	v_pk_mul_f32 v[36:37], v[204:205], v[82:83] op_sel:[0,1] op_sel_hi:[1,0]
	v_add_f32_e32 v1, v68, v1
	v_sub_f32_e32 v36, v36, v37
	v_add_f32_e32 v42, v36, v70
	v_pk_mul_f32 v[36:37], v[204:205], v[82:83]
	v_cndmask_b32_e64 v42, v70, v42, s[10:11]
	v_add_f32_e32 v36, v37, v36
	v_add_f32_e32 v38, v36, v78
	v_pk_mul_f32 v[36:37], v[206:207], v[84:85] op_sel:[0,1] op_sel_hi:[1,0]
	v_cndmask_b32_e64 v41, v69, v41, s[10:11]
	v_sub_f32_e32 v36, v36, v37
	v_add_f32_e32 v43, v36, v71
	v_pk_mul_f32 v[36:37], v[206:207], v[84:85]
	v_cndmask_b32_e64 v43, v71, v43, s[10:11]
	v_add_f32_e32 v36, v37, v36
	v_add_f32_e32 v36, v36, v79
	v_cndmask_b32_e64 v39, v79, v36, s[10:11]
	v_cndmask_b32_e64 v37, v77, v86, s[10:11]
	v_cndmask_b32_e64 v36, v76, v40, s[10:11]
	v_cndmask_b32_e64 v40, v68, v1, s[10:11]
	v_mov_b32_dpp v71, v37 row_shr:1 row_mask:0xf bank_mask:0xf bound_ctrl:1
	v_mov_b32_dpp v70, v36 row_shr:1 row_mask:0xf bank_mask:0xf bound_ctrl:1
	v_mov_b32_e32 v86, v72
	v_mov_b32_e32 v87, v74
	v_mov_b32_dpp v68, v40 row_shr:1 row_mask:0xf bank_mask:0xf bound_ctrl:1
	v_mov_b32_dpp v69, v41 row_shr:1 row_mask:0xf bank_mask:0xf bound_ctrl:1
	v_pk_mul_f32 v[88:89], v[86:87], v[70:71]
	v_mov_b32_e32 v91, v75
	v_pk_fma_f32 v[88:89], v[90:91], v[68:69], v[88:89]
	v_pk_mul_f32 v[74:75], v[74:75], v[74:75]
	v_pk_mul_f32 v[72:73], v[72:73], v[72:73]
	v_pk_add_f32 v[36:37], v[88:89], v[36:37]
	v_mov_b32_e32 v88, v72
	v_mov_b32_e32 v89, v74
	v_mov_b32_e32 v74, v73
	v_pk_mul_f32 v[70:71], v[90:91], v[70:71]
	v_pk_add_f32 v[72:73], v[88:89], v[74:75] neg_lo:[0,1] neg_hi:[0,1]
	v_pk_add_f32 v[74:75], v[86:87], v[86:87]
	v_pk_fma_f32 v[68:69], v[86:87], v[68:69], v[70:71] neg_lo:[0,0,1] neg_hi:[0,0,1]
	v_pk_mul_f32 v[74:75], v[90:91], v[74:75]
	v_mov_b32_dpp v88, v36 row_shr:2 row_mask:0xf bank_mask:0xf bound_ctrl:1
	v_mov_b32_dpp v89, v37 row_shr:2 row_mask:0xf bank_mask:0xf bound_ctrl:1
	v_pk_add_f32 v[40:41], v[68:69], v[40:41]
	v_pk_mul_f32 v[200:201], v[72:73], v[88:89]
	v_pk_mul_f32 v[70:71], v[74:75], v[88:89]
	v_mov_b32_dpp v68, v40 row_shr:2 row_mask:0xf bank_mask:0xf bound_ctrl:1
	v_mov_b32_dpp v69, v41 row_shr:2 row_mask:0xf bank_mask:0xf bound_ctrl:1
	v_pk_fma_f32 v[70:71], v[72:73], v[68:69], v[70:71] neg_lo:[0,0,1] neg_hi:[0,0,1]
	v_pk_fma_f32 v[68:69], v[74:75], v[68:69], v[200:201]
	v_pk_mul_f32 v[208:209], v[74:75], v[74:75]
	v_pk_add_f32 v[210:211], v[72:73], v[72:73]
	v_pk_add_f32 v[36:37], v[36:37], v[68:69]
	v_pk_fma_f32 v[208:209], v[72:73], v[72:73], v[208:209] neg_lo:[0,0,1] neg_hi:[0,0,1]
	v_pk_mul_f32 v[210:211], v[74:75], v[210:211]
	v_pk_add_f32 v[40:41], v[70:71], v[40:41]
	v_mov_b32_dpp v70, v36 row_shr:4 row_mask:0xf bank_mask:0xf bound_ctrl:1
	v_mov_b32_dpp v71, v37 row_shr:4 row_mask:0xf bank_mask:0xf bound_ctrl:1
	v_mov_b32_dpp v68, v40 row_shr:4 row_mask:0xf bank_mask:0xf bound_ctrl:1
	v_mov_b32_dpp v69, v41 row_shr:4 row_mask:0xf bank_mask:0xf bound_ctrl:1
	v_pk_mul_f32 v[72:73], v[210:211], v[70:71]
	v_pk_mul_f32 v[70:71], v[208:209], v[70:71]
	v_pk_fma_f32 v[72:73], v[208:209], v[68:69], v[72:73] neg_lo:[0,0,1] neg_hi:[0,0,1]
	v_pk_fma_f32 v[68:69], v[210:211], v[68:69], v[70:71]
	v_pk_add_f32 v[214:215], v[208:209], v[208:209]
; __device__ __forceinline__ unsigned cvt_pk_bf16(float lo, float hi) { unsigned r; asm("v_cvt_pk_bf16_f32 %0, %1, %2" : "=v"(r) : "v"(lo), "v"(hi)); return r; }
; #define SSM_SCAN_STEP(D, SQ) { _Pragma("unroll") for (int r = 0; r < 4; ++r) { \
;                     const float sr = dppf<DPP_SHR(D)>(Er[r]), si = dppf<DPP_SHR(D)>(Ei[r]); \
;                     Er[r] += mr[r] * sr - mi[r] * si; Ei[r] += mr[r] * si + mi[r] * sr; \
;                     if (SQ) { const float nr = mr[r] * mr[r] - mi[r] * mi[r], ni = 2.f * mr[r] * mi[r]; mr[r] = nr; mi[r] = ni; } } }
; template <bool PASS2>
; __device__ __forceinline__ void ssm_phase(const Params& p, const Frame& F0) {
;     ...
;                 for (int r = 0; r < 4; ++r) { hr[r] = dppf<DPP_ROR(1)>(xs[i][r]); hi[r] = dppf<DPP_ROR(1)>(xs[i + 4][r]);
;                     if (j == 0) { Er[r] += mr[r] * hr[r] - mi[r] * hi[r]; Ei[r] += mr[r] * hi[r] + mi[r] * hr[r]; } }
;     ...
;                 SSM_SCAN_STEP(1, 1) SSM_SCAN_STEP(2, 1) SSM_SCAN_STEP(4, 1) SSM_SCAN_STEP(8, 0)
;     ...
;                 if constexpr (PASS2) {
;                     float vr[4], vi[4];
; #pragma unroll
;                     for (int r = 0; r < 4; ++r) { const float pr_ = dppf<DPP_ROR(1)>(Er[r]), pi_ = dppf<DPP_ROR(1)>(Ei[r]); vr[r] = (j == 0) ? hr[r] : pr_; vi[r] = (j == 0) ? hi[r] : pi_; }
;                     hw[i >> 1][2 * (i & 1)] = cvt_pk_bf16(vr[0], vr[1]); hw[i >> 1][2 * (i & 1) + 1] = cvt_pk_bf16(vr[2], vr[3]);
;                     hw[2 + (i >> 1)][2 * (i & 1)] = cvt_pk_bf16(vi[0], vi[1]); hw[2 + (i >> 1)][2 * (i & 1) + 1] = cvt_pk_bf16(vi[2], vi[3]);
	v_pk_add_f32 v[68:69], v[36:37], v[68:69]
	v_pk_mul_f32 v[212:213], v[210:211], v[210:211]
	v_pk_mul_f32 v[214:215], v[210:211], v[214:215]
	v_pk_add_f32 v[40:41], v[40:41], v[72:73]
	v_mov_b32_dpp v72, v68 row_shr:8 row_mask:0xf bank_mask:0xf bound_ctrl:1
	v_mov_b32_dpp v73, v69 row_shr:8 row_mask:0xf bank_mask:0xf bound_ctrl:1
	v_pk_fma_f32 v[212:213], v[208:209], v[208:209], v[212:213] neg_lo:[0,0,1] neg_hi:[0,0,1]
	v_mov_b32_dpp v70, v40 row_shr:8 row_mask:0xf bank_mask:0xf bound_ctrl:1
	v_mov_b32_dpp v71, v41 row_shr:8 row_mask:0xf bank_mask:0xf bound_ctrl:1
	v_pk_mul_f32 v[36:37], v[214:215], v[72:73]
	v_cndmask_b32_e64 v38, v78, v38, s[10:11]
	v_pk_fma_f32 v[36:37], v[212:213], v[70:71], v[36:37] neg_lo:[0,0,1] neg_hi:[0,0,1]
	v_mov_b32_dpp v79, v39 row_shr:1 row_mask:0xf bank_mask:0xf bound_ctrl:1
	v_pk_add_f32 v[36:37], v[40:41], v[36:37]
	v_pk_mul_f32 v[40:41], v[212:213], v[72:73]
	v_mov_b32_dpp v78, v38 row_shr:1 row_mask:0xf bank_mask:0xf bound_ctrl:1
	v_pk_fma_f32 v[40:41], v[214:215], v[70:71], v[40:41]
	v_mov_b32_dpp v76, v42 row_shr:1 row_mask:0xf bank_mask:0xf bound_ctrl:1
	v_pk_add_f32 v[40:41], v[68:69], v[40:41]
	v_mov_b32_e32 v68, v204
	v_mov_b32_e32 v69, v206
	v_mov_b32_dpp v77, v43 row_shr:1 row_mask:0xf bank_mask:0xf bound_ctrl:1
	v_pk_mul_f32 v[70:71], v[68:69], v[78:79]
	v_mov_b32_e32 v72, v205
	v_mov_b32_e32 v73, v207
	v_pk_fma_f32 v[70:71], v[72:73], v[76:77], v[70:71]
	v_pk_mul_f32 v[74:75], v[204:205], v[204:205]
	v_pk_add_f32 v[38:39], v[70:71], v[38:39]
	v_pk_mul_f32 v[70:71], v[206:207], v[206:207]
	v_mov_b32_e32 v86, v74
	v_mov_b32_e32 v87, v70
	v_mov_b32_e32 v70, v75
	v_pk_add_f32 v[74:75], v[68:69], v[68:69]
	v_pk_add_f32 v[70:71], v[86:87], v[70:71] neg_lo:[0,1] neg_hi:[0,1]
	v_pk_mul_f32 v[74:75], v[72:73], v[74:75]
	v_pk_mul_f32 v[72:73], v[72:73], v[78:79]
	v_mov_b32_dpp v86, v38 row_shr:2 row_mask:0xf bank_mask:0xf bound_ctrl:1
	v_pk_fma_f32 v[68:69], v[68:69], v[76:77], v[72:73] neg_lo:[0,0,1] neg_hi:[0,0,1]
	v_mov_b32_dpp v87, v39 row_shr:2 row_mask:0xf bank_mask:0xf bound_ctrl:1
	v_pk_add_f32 v[42:43], v[68:69], v[42:43]
	v_pk_mul_f32 v[88:89], v[70:71], v[86:87]
	v_pk_mul_f32 v[90:91], v[74:75], v[74:75]
	v_mov_b32_dpp v68, v42 row_shr:2 row_mask:0xf bank_mask:0xf bound_ctrl:1
	v_mov_b32_dpp v69, v43 row_shr:2 row_mask:0xf bank_mask:0xf bound_ctrl:1
	v_pk_mul_f32 v[72:73], v[74:75], v[86:87]
	v_pk_fma_f32 v[90:91], v[70:71], v[70:71], v[90:91] neg_lo:[0,0,1] neg_hi:[0,0,1]
	v_pk_add_f32 v[200:201], v[70:71], v[70:71]
	v_pk_fma_f32 v[70:71], v[70:71], v[68:69], v[72:73] neg_lo:[0,0,1] neg_hi:[0,0,1]
	v_pk_fma_f32 v[68:69], v[74:75], v[68:69], v[88:89]
	v_pk_mul_f32 v[200:201], v[74:75], v[200:201]
	v_pk_add_f32 v[38:39], v[38:39], v[68:69]
	v_pk_add_f32 v[42:43], v[42:43], v[70:71]
	v_pk_add_f32 v[206:207], v[90:91], v[90:91]
	v_mov_b32_dpp v70, v38 row_shr:4 row_mask:0xf bank_mask:0xf bound_ctrl:1
	v_mov_b32_dpp v71, v39 row_shr:4 row_mask:0xf bank_mask:0xf bound_ctrl:1
	v_mov_b32_dpp v68, v42 row_shr:4 row_mask:0xf bank_mask:0xf bound_ctrl:1
	v_mov_b32_dpp v69, v43 row_shr:4 row_mask:0xf bank_mask:0xf bound_ctrl:1
	v_pk_mul_f32 v[72:73], v[200:201], v[70:71]
	v_pk_mul_f32 v[70:71], v[90:91], v[70:71]
	v_pk_fma_f32 v[72:73], v[90:91], v[68:69], v[72:73] neg_lo:[0,0,1] neg_hi:[0,0,1]
	v_pk_fma_f32 v[68:69], v[200:201], v[68:69], v[70:71]
	v_pk_mul_f32 v[204:205], v[200:201], v[200:201]
	v_pk_add_f32 v[68:69], v[38:39], v[68:69]
	v_pk_mul_f32 v[206:207], v[200:201], v[206:207]
	v_pk_add_f32 v[42:43], v[42:43], v[72:73]
	v_mov_b32_dpp v72, v68 row_shr:8 row_mask:0xf bank_mask:0xf bound_ctrl:1
	v_mov_b32_dpp v73, v69 row_shr:8 row_mask:0xf bank_mask:0xf bound_ctrl:1
	v_pk_fma_f32 v[204:205], v[90:91], v[90:91], v[204:205] neg_lo:[0,0,1] neg_hi:[0,0,1]
	v_mov_b32_dpp v70, v42 row_shr:8 row_mask:0xf bank_mask:0xf bound_ctrl:1
	v_mov_b32_dpp v71, v43 row_shr:8 row_mask:0xf bank_mask:0xf bound_ctrl:1
	v_pk_mul_f32 v[38:39], v[206:207], v[72:73]
	v_mov_b32_dpp v1, v36 row_ror:1 row_mask:0xf bank_mask:0xf bound_ctrl:1
	v_pk_fma_f32 v[38:39], v[204:205], v[70:71], v[38:39] neg_lo:[0,0,1] neg_hi:[0,0,1]
	v_cndmask_b32_e64 v1, v1, v3, s[10:11]
	v_pk_add_f32 v[38:39], v[42:43], v[38:39]
	v_pk_mul_f32 v[42:43], v[204:205], v[72:73]
	v_mov_b32_dpp v3, v37 row_ror:1 row_mask:0xf bank_mask:0xf bound_ctrl:1
	v_pk_fma_f32 v[42:43], v[206:207], v[70:71], v[42:43]
	v_mov_b32_dpp v71, v39 row_ror:1 row_mask:0xf bank_mask:0xf bound_ctrl:1
	v_pk_add_f32 v[42:43], v[68:69], v[42:43]
	v_mov_b32_dpp v68, v40 row_ror:1 row_mask:0xf bank_mask:0xf bound_ctrl:1
	v_cndmask_b32_e64 v2, v68, v2, s[10:11]
	v_mov_b32_dpp v69, v38 row_ror:1 row_mask:0xf bank_mask:0xf bound_ctrl:1
	v_mov_b32_dpp v68, v41 row_ror:1 row_mask:0xf bank_mask:0xf bound_ctrl:1
	v_mov_b32_dpp v70, v42 row_ror:1 row_mask:0xf bank_mask:0xf bound_ctrl:1
	v_mov_b32_dpp v72, v43 row_ror:1 row_mask:0xf bank_mask:0xf bound_ctrl:1
	v_cndmask_b32_e64 v68, v68, v80, s[10:11]
	v_cndmask_b32_e64 v69, v69, v83, s[10:11]
	v_cndmask_b32_e64 v70, v70, v82, s[10:11]
	v_cndmask_b32_e64 v71, v71, v85, s[10:11]
	v_cndmask_b32_e64 v74, v72, v84, s[10:11]
	v_cndmask_b32_e64 v3, v3, v81, s[10:11]
	v_cvt_pk_bf16_f32 v72, v1, v3
	v_cvt_pk_bf16_f32 v73, v69, v71
	v_cvt_pk_bf16_f32 v68, v2, v68
	v_cvt_pk_bf16_f32 v69, v70, v74
	ds_read_b128 v[74:77], v105 offset:4096
	ds_read_b128 v[78:81], v105 offset:5120
	ds_read_b128 v[82:85], v105 offset:20480
	ds_read_b128 v[86:89], v105 offset:21504
	v_mov_b32_dpp v3, v28 row_ror:1 row_mask:0xf bank_mask:0xf bound_ctrl:1
	s_and_b32 s98, s3, 0x180
	s_cbranch_scc1 .Lssmw_3
	s_waitcnt vmcnt(4)
; #define SSM_SCAN_STEP(D, SQ) { _Pragma("unroll") for (int r = 0; r < 4; ++r) { \
;                     const float sr = dppf<DPP_SHR(D)>(Er[r]), si = dppf<DPP_SHR(D)>(Ei[r]); \
;                     Er[r] += mr[r] * sr - mi[r] * si; Ei[r] += mr[r] * si + mi[r] * sr; \
;                     if (SQ) { const float nr = mr[r] * mr[r] - mi[r] * mi[r], ni = 2.f * mr[r] * mi[r]; mr[r] = nr; mi[r] = ni; } } }
; template <bool PASS2>
; __device__ __forceinline__ void ssm_phase(const Params& p, const Frame& F0) {
;     ...
;             for (int i = 0; i < 4; ++i) {
;                 __builtin_amdgcn_sched_barrier(0);
;                 f32x4 Er = (f32x4){0.f, 0.f, 0.f, 0.f}, Ei = Er;
; #pragma unroll
;                 for (int ks = 0; ks < 4; ++ks) { Er = __builtin_amdgcn_mfma_f32_16x16x32_bf16(frag[(i * 4 + ks) * 64], uf[ks], Er, 0, 0, 0);
;                                                  Ei = __builtin_amdgcn_mfma_f32_16x16x32_bf16(frag[((i + 4) * 4 + ks) * 64], uf[ks], Ei, 0, 0, 0); }
;                 const f32x4 ma = m1t[8 * i], mb = m1t[8 * i + 1];
;                 float mr[4] = {ma[0], ma[2], mb[0], mb[2]}, mi[4] = {ma[1], ma[3], mb[1], mb[3]};
;                 float hr[4], hi[4];
; #pragma unroll
;                 for (int r = 0; r < 4; ++r) { hr[r] = dppf<DPP_ROR(1)>(xs[i][r]); hi[r] = dppf<DPP_ROR(1)>(xs[i + 4][r]);
;                     if (j == 0) { Er[r] += mr[r] * hr[r] - mi[r] * hi[r]; Ei[r] += mr[r] * hi[r] + mi[r] * hr[r]; } }
;     ...
;                 SSM_SCAN_STEP(1, 1) SSM_SCAN_STEP(2, 1) SSM_SCAN_STEP(4, 1) SSM_SCAN_STEP(8, 0)
.Lssmw_3:
	v_mov_b32_dpp v2, v32 row_ror:1 row_mask:0xf bank_mask:0xf bound_ctrl:1
	s_waitcnt lgkmcnt(3)
	v_mfma_f32_16x16x32_bf16 v[74:77], v[74:77], v[56:59], 0
	s_waitcnt lgkmcnt(1)
	v_mfma_f32_16x16x32_bf16 v[82:85], v[82:85], v[56:59], 0
	v_mfma_f32_16x16x32_bf16 v[74:77], v[78:81], v[52:55], v[74:77]
	ds_read_b128 v[78:81], v105 offset:6144
	s_waitcnt lgkmcnt(1)
	v_mfma_f32_16x16x32_bf16 v[82:85], v[86:89], v[52:55], v[82:85]
	ds_read_b128 v[86:89], v105 offset:22528
	ds_read_b128 v[204:207], v105 offset:7168
	ds_read_b128 v[208:211], v105 offset:23552
	s_waitcnt lgkmcnt(2)
	v_mfma_f32_16x16x32_bf16 v[82:85], v[86:89], v[64:67], v[82:85]
	v_mov_b32_dpp v87, v30 row_ror:1 row_mask:0xf bank_mask:0xf bound_ctrl:1
	v_mov_b32_dpp v86, v34 row_ror:1 row_mask:0xf bank_mask:0xf bound_ctrl:1
	v_mov_b32_dpp v89, v31 row_ror:1 row_mask:0xf bank_mask:0xf bound_ctrl:1
	v_mfma_f32_16x16x32_bf16 v[74:77], v[78:81], v[64:67], v[74:77]
	ds_read_b128 v[78:81], v198 offset:128
	ds_read_b128 v[212:215], v198 offset:144
	v_mov_b32_dpp v88, v35 row_ror:1 row_mask:0xf bank_mask:0xf bound_ctrl:1
	s_waitcnt lgkmcnt(1)
	v_pk_mul_f32 v[70:71], v[78:79], v[2:3] op_sel:[0,1] op_sel_hi:[1,0]
	v_mfma_f32_16x16x32_bf16 v[82:85], v[208:211], v[60:63], v[82:85]
	v_sub_f32_e32 v1, v70, v71
	v_pk_mul_f32 v[70:71], v[78:79], v[2:3]
	v_mov_b32_e32 v91, v80
	v_mfma_f32_16x16x32_bf16 v[74:77], v[204:207], v[60:63], v[74:77]
	v_add_f32_e32 v28, v71, v70
	v_mov_b32_dpp v71, v29 row_ror:1 row_mask:0xf bank_mask:0xf bound_ctrl:1
	v_mov_b32_dpp v70, v33 row_ror:1 row_mask:0xf bank_mask:0xf bound_ctrl:1
	s_nop 0
	v_add_f32_e32 v32, v82, v28
	v_pk_mul_f32 v[28:29], v[80:81], v[70:71] op_sel:[0,1] op_sel_hi:[1,0]
	s_nop 1
	v_add_f32_e32 v1, v74, v1
	v_sub_f32_e32 v28, v28, v29
	v_add_f32_e32 v33, v28, v75
	v_pk_mul_f32 v[28:29], v[80:81], v[70:71]
	v_cndmask_b32_e64 v33, v75, v33, s[10:11]
	v_add_f32_e32 v28, v29, v28
	v_add_f32_e32 v90, v28, v83
	s_waitcnt lgkmcnt(0)
	v_pk_mul_f32 v[28:29], v[212:213], v[86:87] op_sel:[0,1] op_sel_hi:[1,0]
	v_mov_b32_dpp v75, v33 row_shr:1 row_mask:0xf bank_mask:0xf bound_ctrl:1
	v_sub_f32_e32 v28, v28, v29
	v_add_f32_e32 v34, v28, v76
	v_pk_mul_f32 v[28:29], v[212:213], v[86:87]
	v_cndmask_b32_e64 v34, v76, v34, s[10:11]
	v_add_f32_e32 v28, v29, v28
	v_add_f32_e32 v30, v28, v84
	v_pk_mul_f32 v[28:29], v[214:215], v[88:89] op_sel:[0,1] op_sel_hi:[1,0]
	v_mov_b32_e32 v204, v79
	v_sub_f32_e32 v28, v28, v29
	v_add_f32_e32 v35, v28, v77
	v_pk_mul_f32 v[28:29], v[214:215], v[88:89]
	v_cndmask_b32_e64 v35, v77, v35, s[10:11]
	v_add_f32_e32 v28, v29, v28
	v_add_f32_e32 v28, v28, v85
	v_cndmask_b32_e64 v31, v85, v28, s[10:11]
	v_cndmask_b32_e64 v29, v83, v90, s[10:11]
	v_cndmask_b32_e64 v28, v82, v32, s[10:11]
	v_cndmask_b32_e64 v32, v74, v1, s[10:11]
	v_mov_b32_dpp v77, v29 row_shr:1 row_mask:0xf bank_mask:0xf bound_ctrl:1
	v_mov_b32_dpp v76, v28 row_shr:1 row_mask:0xf bank_mask:0xf bound_ctrl:1
	v_mov_b32_e32 v90, v78
	v_mov_b32_dpp v74, v32 row_shr:1 row_mask:0xf bank_mask:0xf bound_ctrl:1
	v_pk_mul_f32 v[200:201], v[90:91], v[76:77]
	v_mov_b32_e32 v205, v81
	v_pk_fma_f32 v[200:201], v[204:205], v[74:75], v[200:201]
	v_pk_mul_f32 v[80:81], v[80:81], v[80:81]
	v_pk_mul_f32 v[78:79], v[78:79], v[78:79]
	v_pk_add_f32 v[28:29], v[200:201], v[28:29]
	v_mov_b32_e32 v200, v78
	v_mov_b32_e32 v201, v80
	v_mov_b32_e32 v80, v79
	v_pk_mul_f32 v[76:77], v[204:205], v[76:77]
	v_pk_add_f32 v[78:79], v[200:201], v[80:81] neg_lo:[0,1] neg_hi:[0,1]
	v_pk_add_f32 v[80:81], v[90:91], v[90:91]
	v_pk_fma_f32 v[74:75], v[90:91], v[74:75], v[76:77] neg_lo:[0,0,1] neg_hi:[0,0,1]
	v_pk_mul_f32 v[80:81], v[204:205], v[80:81]
	v_mov_b32_dpp v200, v28 row_shr:2 row_mask:0xf bank_mask:0xf bound_ctrl:1
	v_mov_b32_dpp v201, v29 row_shr:2 row_mask:0xf bank_mask:0xf bound_ctrl:1
	v_pk_add_f32 v[32:33], v[74:75], v[32:33]
	v_pk_mul_f32 v[206:207], v[78:79], v[200:201]
	v_pk_mul_f32 v[76:77], v[80:81], v[200:201]
	v_mov_b32_dpp v74, v32 row_shr:2 row_mask:0xf bank_mask:0xf bound_ctrl:1
	v_mov_b32_dpp v75, v33 row_shr:2 row_mask:0xf bank_mask:0xf bound_ctrl:1
	v_pk_fma_f32 v[76:77], v[78:79], v[74:75], v[76:77] neg_lo:[0,0,1] neg_hi:[0,0,1]
	v_pk_fma_f32 v[74:75], v[80:81], v[74:75], v[206:207]
	v_pk_mul_f32 v[208:209], v[80:81], v[80:81]
	v_pk_add_f32 v[210:211], v[78:79], v[78:79]
	v_pk_add_f32 v[28:29], v[28:29], v[74:75]
	v_pk_fma_f32 v[208:209], v[78:79], v[78:79], v[208:209] neg_lo:[0,0,1] neg_hi:[0,0,1]
	v_pk_mul_f32 v[210:211], v[80:81], v[210:211]
	v_pk_add_f32 v[32:33], v[76:77], v[32:33]
	v_mov_b32_dpp v76, v28 row_shr:4 row_mask:0xf bank_mask:0xf bound_ctrl:1
	v_mov_b32_dpp v77, v29 row_shr:4 row_mask:0xf bank_mask:0xf bound_ctrl:1
	v_mov_b32_dpp v74, v32 row_shr:4 row_mask:0xf bank_mask:0xf bound_ctrl:1
	v_mov_b32_dpp v75, v33 row_shr:4 row_mask:0xf bank_mask:0xf bound_ctrl:1
	v_pk_mul_f32 v[78:79], v[210:211], v[76:77]
	v_pk_mul_f32 v[76:77], v[208:209], v[76:77]
	v_pk_fma_f32 v[78:79], v[208:209], v[74:75], v[78:79] neg_lo:[0,0,1] neg_hi:[0,0,1]
	v_pk_fma_f32 v[74:75], v[210:211], v[74:75], v[76:77]
	v_pk_add_f32 v[218:219], v[208:209], v[208:209]
	v_pk_add_f32 v[74:75], v[28:29], v[74:75]
	v_pk_mul_f32 v[216:217], v[210:211], v[210:211]
	v_pk_mul_f32 v[218:219], v[210:211], v[218:219]
	v_pk_add_f32 v[32:33], v[32:33], v[78:79]
	v_mov_b32_dpp v78, v74 row_shr:8 row_mask:0xf bank_mask:0xf bound_ctrl:1
	v_mov_b32_dpp v79, v75 row_shr:8 row_mask:0xf bank_mask:0xf bound_ctrl:1
	v_pk_fma_f32 v[216:217], v[208:209], v[208:209], v[216:217] neg_lo:[0,0,1] neg_hi:[0,0,1]
	v_mov_b32_dpp v76, v32 row_shr:8 row_mask:0xf bank_mask:0xf bound_ctrl:1
; __device__ __forceinline__ unsigned cvt_pk_bf16(float lo, float hi) { unsigned r; asm("v_cvt_pk_bf16_f32 %0, %1, %2" : "=v"(r) : "v"(lo), "v"(hi)); return r; }
; #define SSM_SCAN_STEP(D, SQ) { _Pragma("unroll") for (int r = 0; r < 4; ++r) { \
;                     const float sr = dppf<DPP_SHR(D)>(Er[r]), si = dppf<DPP_SHR(D)>(Ei[r]); \
;                     Er[r] += mr[r] * sr - mi[r] * si; Ei[r] += mr[r] * si + mi[r] * sr; \
;                     if (SQ) { const float nr = mr[r] * mr[r] - mi[r] * mi[r], ni = 2.f * mr[r] * mi[r]; mr[r] = nr; mi[r] = ni; } } }
; template <bool PASS2>
; __device__ __forceinline__ void ssm_phase(const Params& p, const Frame& F0) {
;     ...
;                 SSM_SCAN_STEP(1, 1) SSM_SCAN_STEP(2, 1) SSM_SCAN_STEP(4, 1) SSM_SCAN_STEP(8, 0)
;     ...
;                 if constexpr (PASS2) {
;                     float vr[4], vi[4];
; #pragma unroll
;                     for (int r = 0; r < 4; ++r) { const float pr_ = dppf<DPP_ROR(1)>(Er[r]), pi_ = dppf<DPP_ROR(1)>(Ei[r]); vr[r] = (j == 0) ? hr[r] : pr_; vi[r] = (j == 0) ? hi[r] : pi_; }
;                     hw[i >> 1][2 * (i & 1)] = cvt_pk_bf16(vr[0], vr[1]); hw[i >> 1][2 * (i & 1) + 1] = cvt_pk_bf16(vr[2], vr[3]);
;                     hw[2 + (i >> 1)][2 * (i & 1)] = cvt_pk_bf16(vi[0], vi[1]); hw[2 + (i >> 1)][2 * (i & 1) + 1] = cvt_pk_bf16(vi[2], vi[3]);
	v_mov_b32_dpp v77, v33 row_shr:8 row_mask:0xf bank_mask:0xf bound_ctrl:1
	v_pk_mul_f32 v[28:29], v[218:219], v[78:79]
	v_cndmask_b32_e64 v30, v84, v30, s[10:11]
	v_pk_fma_f32 v[28:29], v[216:217], v[76:77], v[28:29] neg_lo:[0,0,1] neg_hi:[0,0,1]
	v_mov_b32_dpp v85, v31 row_shr:1 row_mask:0xf bank_mask:0xf bound_ctrl:1
	v_pk_add_f32 v[28:29], v[32:33], v[28:29]
	v_pk_mul_f32 v[32:33], v[216:217], v[78:79]
	v_mov_b32_dpp v84, v30 row_shr:1 row_mask:0xf bank_mask:0xf bound_ctrl:1
	v_pk_fma_f32 v[32:33], v[218:219], v[76:77], v[32:33]
	v_mov_b32_dpp v82, v34 row_shr:1 row_mask:0xf bank_mask:0xf bound_ctrl:1
	v_pk_add_f32 v[32:33], v[74:75], v[32:33]
	v_mov_b32_e32 v74, v212
	v_mov_b32_e32 v75, v214
	v_mov_b32_dpp v83, v35 row_shr:1 row_mask:0xf bank_mask:0xf bound_ctrl:1
	v_pk_mul_f32 v[76:77], v[74:75], v[84:85]
	v_mov_b32_e32 v78, v213
	v_mov_b32_e32 v79, v215
	v_pk_fma_f32 v[76:77], v[78:79], v[82:83], v[76:77]
	v_pk_mul_f32 v[80:81], v[212:213], v[212:213]
	v_pk_add_f32 v[30:31], v[76:77], v[30:31]
	v_pk_mul_f32 v[76:77], v[214:215], v[214:215]
	v_mov_b32_e32 v90, v80
	v_mov_b32_e32 v91, v76
	v_mov_b32_e32 v76, v81
	v_pk_add_f32 v[80:81], v[74:75], v[74:75]
	v_pk_add_f32 v[76:77], v[90:91], v[76:77] neg_lo:[0,1] neg_hi:[0,1]
	v_pk_mul_f32 v[80:81], v[78:79], v[80:81]
	v_pk_mul_f32 v[78:79], v[78:79], v[84:85]
	v_mov_b32_dpp v90, v30 row_shr:2 row_mask:0xf bank_mask:0xf bound_ctrl:1
	v_pk_fma_f32 v[74:75], v[74:75], v[82:83], v[78:79] neg_lo:[0,0,1] neg_hi:[0,0,1]
	v_mov_b32_dpp v91, v31 row_shr:2 row_mask:0xf bank_mask:0xf bound_ctrl:1
	v_pk_add_f32 v[34:35], v[74:75], v[34:35]
	v_pk_mul_f32 v[200:201], v[76:77], v[90:91]
	v_pk_mul_f32 v[204:205], v[80:81], v[80:81]
	v_mov_b32_dpp v74, v34 row_shr:2 row_mask:0xf bank_mask:0xf bound_ctrl:1
	v_mov_b32_dpp v75, v35 row_shr:2 row_mask:0xf bank_mask:0xf bound_ctrl:1
	v_pk_mul_f32 v[78:79], v[80:81], v[90:91]
	v_pk_fma_f32 v[204:205], v[76:77], v[76:77], v[204:205] neg_lo:[0,0,1] neg_hi:[0,0,1]
	v_pk_add_f32 v[206:207], v[76:77], v[76:77]
	v_pk_fma_f32 v[76:77], v[76:77], v[74:75], v[78:79] neg_lo:[0,0,1] neg_hi:[0,0,1]
	v_pk_fma_f32 v[74:75], v[80:81], v[74:75], v[200:201]
	v_pk_mul_f32 v[206:207], v[80:81], v[206:207]
	v_pk_add_f32 v[30:31], v[30:31], v[74:75]
	v_pk_add_f32 v[34:35], v[34:35], v[76:77]
	v_pk_add_f32 v[210:211], v[204:205], v[204:205]
	v_mov_b32_dpp v76, v30 row_shr:4 row_mask:0xf bank_mask:0xf bound_ctrl:1
	v_mov_b32_dpp v77, v31 row_shr:4 row_mask:0xf bank_mask:0xf bound_ctrl:1
	v_mov_b32_dpp v74, v34 row_shr:4 row_mask:0xf bank_mask:0xf bound_ctrl:1
	v_mov_b32_dpp v75, v35 row_shr:4 row_mask:0xf bank_mask:0xf bound_ctrl:1
	v_pk_mul_f32 v[78:79], v[206:207], v[76:77]
	v_pk_mul_f32 v[76:77], v[204:205], v[76:77]
	v_pk_fma_f32 v[78:79], v[204:205], v[74:75], v[78:79] neg_lo:[0,0,1] neg_hi:[0,0,1]
	v_pk_fma_f32 v[74:75], v[206:207], v[74:75], v[76:77]
	v_pk_mul_f32 v[208:209], v[206:207], v[206:207]
	v_pk_add_f32 v[74:75], v[30:31], v[74:75]
	v_pk_mul_f32 v[210:211], v[206:207], v[210:211]
	v_pk_add_f32 v[34:35], v[34:35], v[78:79]
	v_mov_b32_dpp v78, v74 row_shr:8 row_mask:0xf bank_mask:0xf bound_ctrl:1
	v_mov_b32_dpp v79, v75 row_shr:8 row_mask:0xf bank_mask:0xf bound_ctrl:1
	v_pk_fma_f32 v[208:209], v[204:205], v[204:205], v[208:209] neg_lo:[0,0,1] neg_hi:[0,0,1]
	v_mov_b32_dpp v76, v34 row_shr:8 row_mask:0xf bank_mask:0xf bound_ctrl:1
	v_mov_b32_dpp v77, v35 row_shr:8 row_mask:0xf bank_mask:0xf bound_ctrl:1
	v_pk_mul_f32 v[30:31], v[210:211], v[78:79]
	v_mov_b32_dpp v1, v28 row_ror:1 row_mask:0xf bank_mask:0xf bound_ctrl:1
	v_pk_fma_f32 v[30:31], v[208:209], v[76:77], v[30:31] neg_lo:[0,0,1] neg_hi:[0,0,1]
	v_cndmask_b32_e64 v1, v1, v3, s[10:11]
	v_pk_add_f32 v[30:31], v[34:35], v[30:31]
	v_pk_mul_f32 v[34:35], v[208:209], v[78:79]
	v_mov_b32_dpp v3, v29 row_ror:1 row_mask:0xf bank_mask:0xf bound_ctrl:1
	v_pk_fma_f32 v[34:35], v[210:211], v[76:77], v[34:35]
	v_cndmask_b32_e64 v3, v3, v71, s[10:11]
	v_pk_add_f32 v[34:35], v[74:75], v[34:35]
	v_mov_b32_dpp v74, v32 row_ror:1 row_mask:0xf bank_mask:0xf bound_ctrl:1
	v_cndmask_b32_e64 v2, v74, v2, s[10:11]
	v_mov_b32_dpp v71, v30 row_ror:1 row_mask:0xf bank_mask:0xf bound_ctrl:1
	v_mov_b32_dpp v74, v33 row_ror:1 row_mask:0xf bank_mask:0xf bound_ctrl:1
	v_cndmask_b32_e64 v70, v74, v70, s[10:11]
	v_mov_b32_dpp v75, v35 row_ror:1 row_mask:0xf bank_mask:0xf bound_ctrl:1
	v_mov_b32_dpp v74, v34 row_ror:1 row_mask:0xf bank_mask:0xf bound_ctrl:1
	v_cndmask_b32_e64 v76, v74, v86, s[10:11]
	v_cndmask_b32_e64 v71, v71, v87, s[10:11]
	v_mov_b32_dpp v74, v31 row_ror:1 row_mask:0xf bank_mask:0xf bound_ctrl:1
	v_cndmask_b32_e64 v77, v74, v89, s[10:11]
	v_cndmask_b32_e64 v78, v75, v88, s[10:11]
	v_cvt_pk_bf16_f32 v74, v1, v3
	v_cvt_pk_bf16_f32 v75, v71, v77
	v_cvt_pk_bf16_f32 v70, v2, v70
	v_cvt_pk_bf16_f32 v71, v76, v78
	ds_read_b128 v[76:79], v105 offset:8192
	ds_read_b128 v[80:83], v105 offset:9216
	ds_read_b128 v[84:87], v105 offset:24576
	ds_read_b128 v[88:91], v105 offset:25600
	s_and_b32 s98, s3, 0x180
	s_cbranch_scc1 .Lssmw_4
	s_waitcnt vmcnt(3)
.Lssmw_4:
	v_mov_b32_dpp v3, v20 row_ror:1 row_mask:0xf bank_mask:0xf bound_ctrl:1
	s_and_b32 s98, s3, 0x180
	s_cbranch_scc1 .Lssmw_5
	s_waitcnt vmcnt(1)
; #define SSM_SCAN_STEP(D, SQ) { _Pragma("unroll") for (int r = 0; r < 4; ++r) { \
;                     const float sr = dppf<DPP_SHR(D)>(Er[r]), si = dppf<DPP_SHR(D)>(Ei[r]); \
;                     Er[r] += mr[r] * sr - mi[r] * si; Ei[r] += mr[r] * si + mi[r] * sr; \
;                     if (SQ) { const float nr = mr[r] * mr[r] - mi[r] * mi[r], ni = 2.f * mr[r] * mi[r]; mr[r] = nr; mi[r] = ni; } } }
; template <bool PASS2>
; __device__ __forceinline__ void ssm_phase(const Params& p, const Frame& F0) {
;     ...
;             for (int i = 0; i < 4; ++i) {
;                 __builtin_amdgcn_sched_barrier(0);
;                 f32x4 Er = (f32x4){0.f, 0.f, 0.f, 0.f}, Ei = Er;
; #pragma unroll
;                 for (int ks = 0; ks < 4; ++ks) { Er = __builtin_amdgcn_mfma_f32_16x16x32_bf16(frag[(i * 4 + ks) * 64], uf[ks], Er, 0, 0, 0);
;                                                  Ei = __builtin_amdgcn_mfma_f32_16x16x32_bf16(frag[((i + 4) * 4 + ks) * 64], uf[ks], Ei, 0, 0, 0); }
;                 const f32x4 ma = m1t[8 * i], mb = m1t[8 * i + 1];
;                 float mr[4] = {ma[0], ma[2], mb[0], mb[2]}, mi[4] = {ma[1], ma[3], mb[1], mb[3]};
;                 float hr[4], hi[4];
; #pragma unroll
;                 for (int r = 0; r < 4; ++r) { hr[r] = dppf<DPP_ROR(1)>(xs[i][r]); hi[r] = dppf<DPP_ROR(1)>(xs[i + 4][r]);
;                     if (j == 0) { Er[r] += mr[r] * hr[r] - mi[r] * hi[r]; Ei[r] += mr[r] * hi[r] + mi[r] * hr[r]; } }
;     ...
;                 SSM_SCAN_STEP(1, 1) SSM_SCAN_STEP(2, 1) SSM_SCAN_STEP(4, 1) SSM_SCAN_STEP(8, 0)
.Lssmw_5:
	v_mov_b32_dpp v2, v24 row_ror:1 row_mask:0xf bank_mask:0xf bound_ctrl:1
	s_waitcnt lgkmcnt(3)
	v_mfma_f32_16x16x32_bf16 v[76:79], v[76:79], v[56:59], 0
	v_mov_b32_dpp v201, v23 row_ror:1 row_mask:0xf bank_mask:0xf bound_ctrl:1
	v_mov_b32_dpp v200, v27 row_ror:1 row_mask:0xf bank_mask:0xf bound_ctrl:1
	s_waitcnt lgkmcnt(1)
	v_mfma_f32_16x16x32_bf16 v[84:87], v[84:87], v[56:59], 0
	v_mfma_f32_16x16x32_bf16 v[76:79], v[80:83], v[52:55], v[76:79]
	ds_read_b128 v[80:83], v105 offset:10240
	s_waitcnt lgkmcnt(1)
	v_mfma_f32_16x16x32_bf16 v[84:87], v[88:91], v[52:55], v[84:87]
	ds_read_b128 v[88:91], v105 offset:26624
	ds_read_b128 v[204:207], v105 offset:11264
	ds_read_b128 v[208:211], v105 offset:27648
	s_waitcnt lgkmcnt(2)
	v_mfma_f32_16x16x32_bf16 v[84:87], v[88:91], v[64:67], v[84:87]
	v_mov_b32_dpp v91, v22 row_ror:1 row_mask:0xf bank_mask:0xf bound_ctrl:1
	v_mov_b32_dpp v90, v26 row_ror:1 row_mask:0xf bank_mask:0xf bound_ctrl:1
	v_mfma_f32_16x16x32_bf16 v[76:79], v[80:83], v[64:67], v[76:79]
	ds_read_b128 v[80:83], v198 offset:256
	ds_read_b128 v[212:215], v198 offset:272
	s_waitcnt lgkmcnt(1)
	v_pk_mul_f32 v[88:89], v[80:81], v[2:3] op_sel:[0,1] op_sel_hi:[1,0]
	v_mfma_f32_16x16x32_bf16 v[84:87], v[208:211], v[60:63], v[84:87]
	v_sub_f32_e32 v1, v88, v89
	v_pk_mul_f32 v[88:89], v[80:81], v[2:3]
	v_mov_b32_e32 v208, v81
	v_mfma_f32_16x16x32_bf16 v[76:79], v[204:207], v[60:63], v[76:79]
	v_add_f32_e32 v20, v89, v88
	v_mov_b32_dpp v89, v21 row_ror:1 row_mask:0xf bank_mask:0xf bound_ctrl:1
	v_mov_b32_dpp v88, v25 row_ror:1 row_mask:0xf bank_mask:0xf bound_ctrl:1
	s_nop 0
	v_add_f32_e32 v24, v84, v20
	v_pk_mul_f32 v[20:21], v[82:83], v[88:89] op_sel:[0,1] op_sel_hi:[1,0]
	s_nop 1
	v_add_f32_e32 v1, v76, v1
	v_sub_f32_e32 v20, v20, v21
	v_add_f32_e32 v25, v20, v77
	v_pk_mul_f32 v[20:21], v[82:83], v[88:89]
	v_cndmask_b32_e64 v25, v77, v25, s[10:11]
	v_add_f32_e32 v20, v21, v20
	v_add_f32_e32 v199, v20, v85
	s_waitcnt lgkmcnt(0)
	v_pk_mul_f32 v[20:21], v[212:213], v[90:91] op_sel:[0,1] op_sel_hi:[1,0]
	v_mov_b32_e32 v204, v80
	v_sub_f32_e32 v20, v20, v21
	v_add_f32_e32 v26, v20, v78
	v_pk_mul_f32 v[20:21], v[212:213], v[90:91]
	v_cndmask_b32_e64 v26, v78, v26, s[10:11]
	v_add_f32_e32 v20, v21, v20
	v_add_f32_e32 v22, v20, v86
	v_pk_mul_f32 v[20:21], v[214:215], v[200:201] op_sel:[0,1] op_sel_hi:[1,0]
	v_mov_b32_e32 v205, v82
	v_sub_f32_e32 v20, v20, v21
	v_add_f32_e32 v27, v20, v79
	v_pk_mul_f32 v[20:21], v[214:215], v[200:201]
	v_cndmask_b32_e64 v27, v79, v27, s[10:11]
	v_add_f32_e32 v20, v21, v20
	v_add_f32_e32 v20, v20, v87
	v_cndmask_b32_e64 v23, v87, v20, s[10:11]
	v_cndmask_b32_e64 v21, v85, v199, s[10:11]
	v_cndmask_b32_e64 v20, v84, v24, s[10:11]
	v_cndmask_b32_e64 v24, v76, v1, s[10:11]
	v_mov_b32_dpp v79, v21 row_shr:1 row_mask:0xf bank_mask:0xf bound_ctrl:1
	v_mov_b32_dpp v78, v20 row_shr:1 row_mask:0xf bank_mask:0xf bound_ctrl:1
	v_mov_b32_dpp v76, v24 row_shr:1 row_mask:0xf bank_mask:0xf bound_ctrl:1
	v_mov_b32_dpp v77, v25 row_shr:1 row_mask:0xf bank_mask:0xf bound_ctrl:1
	v_pk_mul_f32 v[206:207], v[204:205], v[78:79]
	v_mov_b32_e32 v209, v83
	v_pk_fma_f32 v[206:207], v[208:209], v[76:77], v[206:207]
	v_pk_mul_f32 v[82:83], v[82:83], v[82:83]
	v_pk_mul_f32 v[80:81], v[80:81], v[80:81]
	v_pk_add_f32 v[20:21], v[206:207], v[20:21]
	v_mov_b32_e32 v206, v80
	v_mov_b32_e32 v207, v82
	v_mov_b32_e32 v82, v81
	v_pk_mul_f32 v[78:79], v[208:209], v[78:79]
	v_pk_add_f32 v[80:81], v[206:207], v[82:83] neg_lo:[0,1] neg_hi:[0,1]
	v_pk_add_f32 v[82:83], v[204:205], v[204:205]
	v_pk_fma_f32 v[76:77], v[204:205], v[76:77], v[78:79] neg_lo:[0,0,1] neg_hi:[0,0,1]
	v_pk_mul_f32 v[82:83], v[208:209], v[82:83]
	v_mov_b32_dpp v206, v20 row_shr:2 row_mask:0xf bank_mask:0xf bound_ctrl:1
	v_mov_b32_dpp v207, v21 row_shr:2 row_mask:0xf bank_mask:0xf bound_ctrl:1
	v_pk_add_f32 v[24:25], v[76:77], v[24:25]
	v_pk_mul_f32 v[210:211], v[80:81], v[206:207]
	v_pk_mul_f32 v[78:79], v[82:83], v[206:207]
	v_mov_b32_dpp v76, v24 row_shr:2 row_mask:0xf bank_mask:0xf bound_ctrl:1
	v_mov_b32_dpp v77, v25 row_shr:2 row_mask:0xf bank_mask:0xf bound_ctrl:1
	v_pk_fma_f32 v[78:79], v[80:81], v[76:77], v[78:79] neg_lo:[0,0,1] neg_hi:[0,0,1]
	v_pk_fma_f32 v[76:77], v[82:83], v[76:77], v[210:211]
	v_pk_mul_f32 v[216:217], v[82:83], v[82:83]
	v_pk_add_f32 v[218:219], v[80:81], v[80:81]
	v_pk_add_f32 v[20:21], v[20:21], v[76:77]
	v_pk_fma_f32 v[216:217], v[80:81], v[80:81], v[216:217] neg_lo:[0,0,1] neg_hi:[0,0,1]
	v_pk_mul_f32 v[218:219], v[82:83], v[218:219]
	v_pk_add_f32 v[24:25], v[78:79], v[24:25]
	v_mov_b32_dpp v78, v20 row_shr:4 row_mask:0xf bank_mask:0xf bound_ctrl:1
	v_mov_b32_dpp v79, v21 row_shr:4 row_mask:0xf bank_mask:0xf bound_ctrl:1
	v_mov_b32_dpp v76, v24 row_shr:4 row_mask:0xf bank_mask:0xf bound_ctrl:1
	v_mov_b32_dpp v77, v25 row_shr:4 row_mask:0xf bank_mask:0xf bound_ctrl:1
	v_pk_mul_f32 v[80:81], v[218:219], v[78:79]
	v_pk_mul_f32 v[78:79], v[216:217], v[78:79]
	v_pk_fma_f32 v[80:81], v[216:217], v[76:77], v[80:81] neg_lo:[0,0,1] neg_hi:[0,0,1]
	v_pk_fma_f32 v[76:77], v[218:219], v[76:77], v[78:79]
	v_pk_add_f32 v[222:223], v[216:217], v[216:217]
	v_pk_add_f32 v[76:77], v[20:21], v[76:77]
	v_pk_mul_f32 v[220:221], v[218:219], v[218:219]
	v_pk_mul_f32 v[222:223], v[218:219], v[222:223]
	v_pk_add_f32 v[24:25], v[24:25], v[80:81]
	v_mov_b32_dpp v80, v76 row_shr:8 row_mask:0xf bank_mask:0xf bound_ctrl:1
	v_mov_b32_dpp v81, v77 row_shr:8 row_mask:0xf bank_mask:0xf bound_ctrl:1
	v_pk_fma_f32 v[220:221], v[216:217], v[216:217], v[220:221] neg_lo:[0,0,1] neg_hi:[0,0,1]
	v_mov_b32_dpp v78, v24 row_shr:8 row_mask:0xf bank_mask:0xf bound_ctrl:1
; __device__ __forceinline__ unsigned cvt_pk_bf16(float lo, float hi) { unsigned r; asm("v_cvt_pk_bf16_f32 %0, %1, %2" : "=v"(r) : "v"(lo), "v"(hi)); return r; }
; #define SSM_SCAN_STEP(D, SQ) { _Pragma("unroll") for (int r = 0; r < 4; ++r) { \
;                     const float sr = dppf<DPP_SHR(D)>(Er[r]), si = dppf<DPP_SHR(D)>(Ei[r]); \
;                     Er[r] += mr[r] * sr - mi[r] * si; Ei[r] += mr[r] * si + mi[r] * sr; \
;                     if (SQ) { const float nr = mr[r] * mr[r] - mi[r] * mi[r], ni = 2.f * mr[r] * mi[r]; mr[r] = nr; mi[r] = ni; } } }
; template <bool PASS2>
; __device__ __forceinline__ void ssm_phase(const Params& p, const Frame& F0) {
;     ...
;                 for (int r = 0; r < 4; ++r) { hr[r] = dppf<DPP_ROR(1)>(xs[i][r]); hi[r] = dppf<DPP_ROR(1)>(xs[i + 4][r]);
;                     if (j == 0) { Er[r] += mr[r] * hr[r] - mi[r] * hi[r]; Ei[r] += mr[r] * hi[r] + mi[r] * hr[r]; } }
;     ...
;                 SSM_SCAN_STEP(1, 1) SSM_SCAN_STEP(2, 1) SSM_SCAN_STEP(4, 1) SSM_SCAN_STEP(8, 0)
;     ...
;                 if constexpr (PASS2) {
;                     float vr[4], vi[4];
; #pragma unroll
;                     for (int r = 0; r < 4; ++r) { const float pr_ = dppf<DPP_ROR(1)>(Er[r]), pi_ = dppf<DPP_ROR(1)>(Ei[r]); vr[r] = (j == 0) ? hr[r] : pr_; vi[r] = (j == 0) ? hi[r] : pi_; }
;                     hw[i >> 1][2 * (i & 1)] = cvt_pk_bf16(vr[0], vr[1]); hw[i >> 1][2 * (i & 1) + 1] = cvt_pk_bf16(vr[2], vr[3]);
;                     hw[2 + (i >> 1)][2 * (i & 1)] = cvt_pk_bf16(vi[0], vi[1]); hw[2 + (i >> 1)][2 * (i & 1) + 1] = cvt_pk_bf16(vi[2], vi[3]);
;                 }
;                 xs[i] = Er; xs[i + 4] = Ei;
	v_mov_b32_dpp v79, v25 row_shr:8 row_mask:0xf bank_mask:0xf bound_ctrl:1
	v_pk_mul_f32 v[20:21], v[222:223], v[80:81]
	v_cndmask_b32_e64 v22, v86, v22, s[10:11]
	v_pk_fma_f32 v[20:21], v[220:221], v[78:79], v[20:21] neg_lo:[0,0,1] neg_hi:[0,0,1]
	v_mov_b32_dpp v87, v23 row_shr:1 row_mask:0xf bank_mask:0xf bound_ctrl:1
	v_pk_add_f32 v[20:21], v[24:25], v[20:21]
	v_pk_mul_f32 v[24:25], v[220:221], v[80:81]
	v_mov_b32_dpp v86, v22 row_shr:1 row_mask:0xf bank_mask:0xf bound_ctrl:1
	v_pk_fma_f32 v[24:25], v[222:223], v[78:79], v[24:25]
	v_mov_b32_dpp v84, v26 row_shr:1 row_mask:0xf bank_mask:0xf bound_ctrl:1
	v_pk_add_f32 v[24:25], v[76:77], v[24:25]
	v_mov_b32_e32 v76, v212
	v_mov_b32_e32 v77, v214
	v_mov_b32_dpp v85, v27 row_shr:1 row_mask:0xf bank_mask:0xf bound_ctrl:1
	v_pk_mul_f32 v[78:79], v[76:77], v[86:87]
	v_mov_b32_e32 v80, v213
	v_mov_b32_e32 v81, v215
	v_pk_fma_f32 v[78:79], v[80:81], v[84:85], v[78:79]
	v_pk_mul_f32 v[82:83], v[212:213], v[212:213]
	v_pk_add_f32 v[22:23], v[78:79], v[22:23]
	v_pk_mul_f32 v[78:79], v[214:215], v[214:215]
	v_mov_b32_e32 v204, v82
	v_mov_b32_e32 v205, v78
	v_mov_b32_e32 v78, v83
	v_pk_add_f32 v[82:83], v[76:77], v[76:77]
	v_pk_add_f32 v[78:79], v[204:205], v[78:79] neg_lo:[0,1] neg_hi:[0,1]
	v_pk_mul_f32 v[82:83], v[80:81], v[82:83]
	v_pk_mul_f32 v[80:81], v[80:81], v[86:87]
	v_mov_b32_dpp v204, v22 row_shr:2 row_mask:0xf bank_mask:0xf bound_ctrl:1
	v_pk_fma_f32 v[76:77], v[76:77], v[84:85], v[80:81] neg_lo:[0,0,1] neg_hi:[0,0,1]
	v_mov_b32_dpp v205, v23 row_shr:2 row_mask:0xf bank_mask:0xf bound_ctrl:1
	v_pk_add_f32 v[26:27], v[76:77], v[26:27]
	v_pk_mul_f32 v[206:207], v[78:79], v[204:205]
	v_pk_mul_f32 v[208:209], v[82:83], v[82:83]
	v_mov_b32_dpp v76, v26 row_shr:2 row_mask:0xf bank_mask:0xf bound_ctrl:1
	v_mov_b32_dpp v77, v27 row_shr:2 row_mask:0xf bank_mask:0xf bound_ctrl:1
	v_pk_mul_f32 v[80:81], v[82:83], v[204:205]
	v_pk_fma_f32 v[208:209], v[78:79], v[78:79], v[208:209] neg_lo:[0,0,1] neg_hi:[0,0,1]
	v_pk_add_f32 v[210:211], v[78:79], v[78:79]
	v_pk_fma_f32 v[78:79], v[78:79], v[76:77], v[80:81] neg_lo:[0,0,1] neg_hi:[0,0,1]
	v_pk_fma_f32 v[76:77], v[82:83], v[76:77], v[206:207]
	v_pk_mul_f32 v[210:211], v[82:83], v[210:211]
	v_pk_add_f32 v[22:23], v[22:23], v[76:77]
	v_pk_add_f32 v[26:27], v[26:27], v[78:79]
	v_pk_add_f32 v[214:215], v[208:209], v[208:209]
	v_mov_b32_dpp v78, v22 row_shr:4 row_mask:0xf bank_mask:0xf bound_ctrl:1
	v_mov_b32_dpp v79, v23 row_shr:4 row_mask:0xf bank_mask:0xf bound_ctrl:1
	v_mov_b32_dpp v76, v26 row_shr:4 row_mask:0xf bank_mask:0xf bound_ctrl:1
	v_mov_b32_dpp v77, v27 row_shr:4 row_mask:0xf bank_mask:0xf bound_ctrl:1
	v_pk_mul_f32 v[80:81], v[210:211], v[78:79]
	v_pk_mul_f32 v[78:79], v[208:209], v[78:79]
	v_pk_fma_f32 v[80:81], v[208:209], v[76:77], v[80:81] neg_lo:[0,0,1] neg_hi:[0,0,1]
	v_pk_fma_f32 v[76:77], v[210:211], v[76:77], v[78:79]
	v_pk_mul_f32 v[212:213], v[210:211], v[210:211]
	v_pk_add_f32 v[76:77], v[22:23], v[76:77]
	v_pk_mul_f32 v[214:215], v[210:211], v[214:215]
	v_pk_add_f32 v[26:27], v[26:27], v[80:81]
	v_mov_b32_dpp v80, v76 row_shr:8 row_mask:0xf bank_mask:0xf bound_ctrl:1
	v_mov_b32_dpp v81, v77 row_shr:8 row_mask:0xf bank_mask:0xf bound_ctrl:1
	v_pk_fma_f32 v[212:213], v[208:209], v[208:209], v[212:213] neg_lo:[0,0,1] neg_hi:[0,0,1]
	v_mov_b32_dpp v78, v26 row_shr:8 row_mask:0xf bank_mask:0xf bound_ctrl:1
	v_mov_b32_dpp v79, v27 row_shr:8 row_mask:0xf bank_mask:0xf bound_ctrl:1
	v_pk_mul_f32 v[22:23], v[214:215], v[80:81]
	v_mov_b32_dpp v1, v20 row_ror:1 row_mask:0xf bank_mask:0xf bound_ctrl:1
	v_pk_fma_f32 v[22:23], v[212:213], v[78:79], v[22:23] neg_lo:[0,0,1] neg_hi:[0,0,1]
	v_cndmask_b32_e64 v1, v1, v3, s[10:11]
	v_pk_add_f32 v[22:23], v[26:27], v[22:23]
	v_pk_mul_f32 v[26:27], v[212:213], v[80:81]
	v_mov_b32_dpp v3, v21 row_ror:1 row_mask:0xf bank_mask:0xf bound_ctrl:1
	v_pk_fma_f32 v[26:27], v[214:215], v[78:79], v[26:27]
	v_mov_b32_dpp v79, v23 row_ror:1 row_mask:0xf bank_mask:0xf bound_ctrl:1
	v_pk_add_f32 v[26:27], v[76:77], v[26:27]
	v_mov_b32_dpp v76, v24 row_ror:1 row_mask:0xf bank_mask:0xf bound_ctrl:1
	v_cndmask_b32_e64 v2, v76, v2, s[10:11]
	v_mov_b32_dpp v77, v22 row_ror:1 row_mask:0xf bank_mask:0xf bound_ctrl:1
	v_mov_b32_dpp v76, v25 row_ror:1 row_mask:0xf bank_mask:0xf bound_ctrl:1
	v_mov_b32_dpp v78, v26 row_ror:1 row_mask:0xf bank_mask:0xf bound_ctrl:1
	v_mov_b32_dpp v80, v27 row_ror:1 row_mask:0xf bank_mask:0xf bound_ctrl:1
	v_cndmask_b32_e64 v76, v76, v88, s[10:11]
	v_cndmask_b32_e64 v77, v77, v91, s[10:11]
	v_cndmask_b32_e64 v78, v78, v90, s[10:11]
	v_cndmask_b32_e64 v79, v79, v201, s[10:11]
	v_cndmask_b32_e64 v82, v80, v200, s[10:11]
	v_cndmask_b32_e64 v3, v3, v89, s[10:11]
	v_cvt_pk_bf16_f32 v80, v1, v3
	v_cvt_pk_bf16_f32 v81, v77, v79
	v_cvt_pk_bf16_f32 v76, v2, v76
	v_cvt_pk_bf16_f32 v77, v78, v82
	ds_read_b128 v[82:85], v105 offset:12288
	ds_read_b128 v[86:89], v105 offset:13312
	ds_read_b128 v[204:207], v105 offset:28672
	ds_read_b128 v[208:211], v105 offset:29696
	v_mov_b32_dpp v3, v44 row_ror:1 row_mask:0xf bank_mask:0xf bound_ctrl:1
	s_and_b32 s98, s3, 0x180
	s_cbranch_scc1 .Lssmw_6
	s_waitcnt vmcnt(0)
; #define SSM_SCAN_STEP(D, SQ) { _Pragma("unroll") for (int r = 0; r < 4; ++r) { \
;                     const float sr = dppf<DPP_SHR(D)>(Er[r]), si = dppf<DPP_SHR(D)>(Ei[r]); \
;                     Er[r] += mr[r] * sr - mi[r] * si; Ei[r] += mr[r] * si + mi[r] * sr; \
;                     if (SQ) { const float nr = mr[r] * mr[r] - mi[r] * mi[r], ni = 2.f * mr[r] * mi[r]; mr[r] = nr; mi[r] = ni; } } }
; template <bool PASS2>
; __device__ __forceinline__ void ssm_phase(const Params& p, const Frame& F0) {
;     ...
;             for (int i = 0; i < 4; ++i) {
;                 __builtin_amdgcn_sched_barrier(0);
;                 f32x4 Er = (f32x4){0.f, 0.f, 0.f, 0.f}, Ei = Er;
; #pragma unroll
;                 for (int ks = 0; ks < 4; ++ks) { Er = __builtin_amdgcn_mfma_f32_16x16x32_bf16(frag[(i * 4 + ks) * 64], uf[ks], Er, 0, 0, 0);
;                                                  Ei = __builtin_amdgcn_mfma_f32_16x16x32_bf16(frag[((i + 4) * 4 + ks) * 64], uf[ks], Ei, 0, 0, 0); }
;                 const f32x4 ma = m1t[8 * i], mb = m1t[8 * i + 1];
;                 float mr[4] = {ma[0], ma[2], mb[0], mb[2]}, mi[4] = {ma[1], ma[3], mb[1], mb[3]};
;                 float hr[4], hi[4];
; #pragma unroll
;                 for (int r = 0; r < 4; ++r) { hr[r] = dppf<DPP_ROR(1)>(xs[i][r]); hi[r] = dppf<DPP_ROR(1)>(xs[i + 4][r]);
;                     if (j == 0) { Er[r] += mr[r] * hr[r] - mi[r] * hi[r]; Ei[r] += mr[r] * hi[r] + mi[r] * hr[r]; } }
;     ...
;                 SSM_SCAN_STEP(1, 1) SSM_SCAN_STEP(2, 1) SSM_SCAN_STEP(4, 1) SSM_SCAN_STEP(8, 0)
.Lssmw_6:
	v_mov_b32_dpp v2, v48 row_ror:1 row_mask:0xf bank_mask:0xf bound_ctrl:1
	s_waitcnt lgkmcnt(3)
	v_mfma_f32_16x16x32_bf16 v[82:85], v[82:85], v[56:59], 0
	v_mov_b32_dpp v91, v46 row_ror:1 row_mask:0xf bank_mask:0xf bound_ctrl:1
	v_mov_b32_dpp v90, v50 row_ror:1 row_mask:0xf bank_mask:0xf bound_ctrl:1
	v_mov_b32_dpp v201, v47 row_ror:1 row_mask:0xf bank_mask:0xf bound_ctrl:1
	s_waitcnt lgkmcnt(1)
	v_mfma_f32_16x16x32_bf16 v[204:207], v[204:207], v[56:59], 0
	v_mov_b32_dpp v200, v51 row_ror:1 row_mask:0xf bank_mask:0xf bound_ctrl:1
	v_mfma_f32_16x16x32_bf16 v[82:85], v[86:89], v[52:55], v[82:85]
	ds_read_b128 v[86:89], v105 offset:14336
	s_waitcnt lgkmcnt(1)
	v_mfma_f32_16x16x32_bf16 v[204:207], v[208:211], v[52:55], v[204:207]
	ds_read_b128 v[208:211], v105 offset:30720
	ds_read_b128 v[212:215], v105 offset:15360
	ds_read_b128 v[216:219], v105 offset:31744
	s_waitcnt lgkmcnt(2)
	v_mfma_f32_16x16x32_bf16 v[204:207], v[208:211], v[64:67], v[204:207]
	v_mfma_f32_16x16x32_bf16 v[82:85], v[86:89], v[64:67], v[82:85]
	ds_read_b128 v[86:89], v198 offset:384
	ds_read_b128 v[220:223], v198 offset:400
	s_waitcnt lgkmcnt(1)
	v_pk_mul_f32 v[78:79], v[86:87], v[2:3] op_sel:[0,1] op_sel_hi:[1,0]
	v_mfma_f32_16x16x32_bf16 v[204:207], v[216:219], v[60:63], v[204:207]
	v_sub_f32_e32 v1, v78, v79
	v_pk_mul_f32 v[78:79], v[86:87], v[2:3]
	v_mov_b32_e32 v208, v86
	v_mfma_f32_16x16x32_bf16 v[82:85], v[212:215], v[60:63], v[82:85]
	v_add_f32_e32 v44, v79, v78
	v_mov_b32_dpp v79, v45 row_ror:1 row_mask:0xf bank_mask:0xf bound_ctrl:1
	v_mov_b32_dpp v78, v49 row_ror:1 row_mask:0xf bank_mask:0xf bound_ctrl:1
	s_nop 0
	v_add_f32_e32 v48, v204, v44
	v_pk_mul_f32 v[44:45], v[88:89], v[78:79] op_sel:[0,1] op_sel_hi:[1,0]
	s_nop 1
	v_add_f32_e32 v1, v82, v1
	v_sub_f32_e32 v44, v44, v45
	v_add_f32_e32 v49, v44, v83
	v_pk_mul_f32 v[44:45], v[88:89], v[78:79]
	v_cndmask_b32_e64 v49, v83, v49, s[10:11]
	v_add_f32_e32 v44, v45, v44
	v_add_f32_e32 v199, v44, v205
	s_waitcnt lgkmcnt(0)
	v_pk_mul_f32 v[44:45], v[220:221], v[90:91] op_sel:[0,1] op_sel_hi:[1,0]
	v_mov_b32_e32 v209, v88
	v_sub_f32_e32 v44, v44, v45
	v_add_f32_e32 v50, v44, v84
	v_pk_mul_f32 v[44:45], v[220:221], v[90:91]
	v_cndmask_b32_e64 v50, v84, v50, s[10:11]
	v_add_f32_e32 v44, v45, v44
	v_add_f32_e32 v46, v44, v206
	v_pk_mul_f32 v[44:45], v[222:223], v[200:201] op_sel:[0,1] op_sel_hi:[1,0]
	v_mov_b32_dpp v83, v49 row_shr:1 row_mask:0xf bank_mask:0xf bound_ctrl:1
	v_sub_f32_e32 v44, v44, v45
	v_add_f32_e32 v51, v44, v85
	v_pk_mul_f32 v[44:45], v[222:223], v[200:201]
	v_cndmask_b32_e64 v51, v85, v51, s[10:11]
	v_add_f32_e32 v44, v45, v44
	v_add_f32_e32 v44, v44, v207
	v_cndmask_b32_e64 v47, v207, v44, s[10:11]
	v_cndmask_b32_e64 v45, v205, v199, s[10:11]
	v_cndmask_b32_e64 v44, v204, v48, s[10:11]
	v_cndmask_b32_e64 v48, v82, v1, s[10:11]
	v_mov_b32_dpp v85, v45 row_shr:1 row_mask:0xf bank_mask:0xf bound_ctrl:1
	v_mov_b32_dpp v84, v44 row_shr:1 row_mask:0xf bank_mask:0xf bound_ctrl:1
	v_mov_b32_dpp v82, v48 row_shr:1 row_mask:0xf bank_mask:0xf bound_ctrl:1
	v_pk_mul_f32 v[210:211], v[208:209], v[84:85]
	v_mov_b32_e32 v212, v87
	v_mov_b32_e32 v213, v89
	v_pk_fma_f32 v[210:211], v[212:213], v[82:83], v[210:211]
	v_pk_mul_f32 v[88:89], v[88:89], v[88:89]
	v_pk_mul_f32 v[86:87], v[86:87], v[86:87]
	v_pk_add_f32 v[44:45], v[210:211], v[44:45]
	v_mov_b32_e32 v210, v86
	v_mov_b32_e32 v211, v88
	v_mov_b32_e32 v88, v87
	v_pk_mul_f32 v[84:85], v[212:213], v[84:85]
	v_pk_add_f32 v[86:87], v[210:211], v[88:89] neg_lo:[0,1] neg_hi:[0,1]
	v_pk_add_f32 v[88:89], v[208:209], v[208:209]
	v_pk_fma_f32 v[82:83], v[208:209], v[82:83], v[84:85] neg_lo:[0,0,1] neg_hi:[0,0,1]
	v_pk_mul_f32 v[88:89], v[212:213], v[88:89]
	v_mov_b32_dpp v210, v44 row_shr:2 row_mask:0xf bank_mask:0xf bound_ctrl:1
	v_mov_b32_dpp v211, v45 row_shr:2 row_mask:0xf bank_mask:0xf bound_ctrl:1
	v_pk_add_f32 v[48:49], v[82:83], v[48:49]
	v_pk_mul_f32 v[214:215], v[86:87], v[210:211]
	v_pk_mul_f32 v[84:85], v[88:89], v[210:211]
	v_mov_b32_dpp v82, v48 row_shr:2 row_mask:0xf bank_mask:0xf bound_ctrl:1
	v_mov_b32_dpp v83, v49 row_shr:2 row_mask:0xf bank_mask:0xf bound_ctrl:1
	v_pk_fma_f32 v[84:85], v[86:87], v[82:83], v[84:85] neg_lo:[0,0,1] neg_hi:[0,0,1]
	v_pk_fma_f32 v[82:83], v[88:89], v[82:83], v[214:215]
	v_pk_mul_f32 v[216:217], v[88:89], v[88:89]
	v_pk_add_f32 v[218:219], v[86:87], v[86:87]
	v_pk_add_f32 v[44:45], v[44:45], v[82:83]
	v_pk_fma_f32 v[216:217], v[86:87], v[86:87], v[216:217] neg_lo:[0,0,1] neg_hi:[0,0,1]
	v_pk_mul_f32 v[218:219], v[88:89], v[218:219]
	v_pk_add_f32 v[48:49], v[84:85], v[48:49]
	v_mov_b32_dpp v84, v44 row_shr:4 row_mask:0xf bank_mask:0xf bound_ctrl:1
	v_mov_b32_dpp v85, v45 row_shr:4 row_mask:0xf bank_mask:0xf bound_ctrl:1
	v_mov_b32_dpp v82, v48 row_shr:4 row_mask:0xf bank_mask:0xf bound_ctrl:1
	v_mov_b32_dpp v83, v49 row_shr:4 row_mask:0xf bank_mask:0xf bound_ctrl:1
	v_pk_mul_f32 v[86:87], v[218:219], v[84:85]
	v_pk_mul_f32 v[84:85], v[216:217], v[84:85]
	v_pk_fma_f32 v[86:87], v[216:217], v[82:83], v[86:87] neg_lo:[0,0,1] neg_hi:[0,0,1]
	v_pk_fma_f32 v[82:83], v[218:219], v[82:83], v[84:85]
	v_pk_add_f32 v[226:227], v[216:217], v[216:217]
	v_pk_add_f32 v[82:83], v[44:45], v[82:83]
	v_pk_mul_f32 v[224:225], v[218:219], v[218:219]
	v_pk_mul_f32 v[226:227], v[218:219], v[226:227]
	v_pk_add_f32 v[48:49], v[48:49], v[86:87]
	v_mov_b32_dpp v86, v82 row_shr:8 row_mask:0xf bank_mask:0xf bound_ctrl:1
	v_mov_b32_dpp v87, v83 row_shr:8 row_mask:0xf bank_mask:0xf bound_ctrl:1
	v_pk_fma_f32 v[224:225], v[216:217], v[216:217], v[224:225] neg_lo:[0,0,1] neg_hi:[0,0,1]
	v_mov_b32_dpp v84, v48 row_shr:8 row_mask:0xf bank_mask:0xf bound_ctrl:1
; __device__ __forceinline__ unsigned cvt_pk_bf16(float lo, float hi) { unsigned r; asm("v_cvt_pk_bf16_f32 %0, %1, %2" : "=v"(r) : "v"(lo), "v"(hi)); return r; }
; #define SSM_SCAN_STEP(D, SQ) { _Pragma("unroll") for (int r = 0; r < 4; ++r) { \
;                     const float sr = dppf<DPP_SHR(D)>(Er[r]), si = dppf<DPP_SHR(D)>(Ei[r]); \
;                     Er[r] += mr[r] * sr - mi[r] * si; Ei[r] += mr[r] * si + mi[r] * sr; \
;                     if (SQ) { const float nr = mr[r] * mr[r] - mi[r] * mi[r], ni = 2.f * mr[r] * mi[r]; mr[r] = nr; mi[r] = ni; } } }
; template <bool PASS2>
; __device__ __forceinline__ void ssm_phase(const Params& p, const Frame& F0) {
;     ...
;                 SSM_SCAN_STEP(1, 1) SSM_SCAN_STEP(2, 1) SSM_SCAN_STEP(4, 1) SSM_SCAN_STEP(8, 0)
;     ...
;                 if constexpr (PASS2) {
;                     float vr[4], vi[4];
; #pragma unroll
;                     for (int r = 0; r < 4; ++r) { const float pr_ = dppf<DPP_ROR(1)>(Er[r]), pi_ = dppf<DPP_ROR(1)>(Ei[r]); vr[r] = (j == 0) ? hr[r] : pr_; vi[r] = (j == 0) ? hi[r] : pi_; }
;                     hw[i >> 1][2 * (i & 1)] = cvt_pk_bf16(vr[0], vr[1]); hw[i >> 1][2 * (i & 1) + 1] = cvt_pk_bf16(vr[2], vr[3]);
;                     hw[2 + (i >> 1)][2 * (i & 1)] = cvt_pk_bf16(vi[0], vi[1]); hw[2 + (i >> 1)][2 * (i & 1) + 1] = cvt_pk_bf16(vi[2], vi[3]);
;                 }
;                 xs[i] = Er; xs[i + 4] = Ei;
;             }
;             __builtin_amdgcn_sched_barrier(0);
;             asm volatile("" ::: "memory");
;             if constexpr (PASS2) {
;                 bf16x8 hf[4];
; #pragma unroll
;                 for (int kap = 0; kap < 4; ++kap) hf[kap] = __builtin_bit_cast(bf16x8, (u32x4){hw[kap][0], hw[kap][1], hw[kap][2], hw[kap][3]});
;                 const f32x4 dv = *(const f32x4*)(p.in[16] + g * 16 + 4 * gq);
; #pragma unroll
;                 for (int t = 0; t < 8; ++t) {
;                     asm volatile("" ::: "memory");
;                     f32x4 y = (f32x4){0.f, 0.f, 0.f, 0.f};
; #pragma unroll
;                     for (int ks = 0; ks < 4; ++ks) y = __builtin_amdgcn_mfma_f32_16x16x32_bf16(frag[(32 + t * 4 + ks) * 64], uf[ks], y, 0, 0, 0);
; #pragma unroll
;                     for (int kap = 0; kap < 4; ++kap) y = __builtin_amdgcn_mfma_f32_16x16x32_bf16(frag[(64 + t * 4 + kap) * 64], hf[kap], y, 0, 0, 0);
	v_mov_b32_dpp v85, v49 row_shr:8 row_mask:0xf bank_mask:0xf bound_ctrl:1
	v_pk_mul_f32 v[44:45], v[226:227], v[86:87]
	v_cndmask_b32_e64 v46, v206, v46, s[10:11]
	v_pk_fma_f32 v[44:45], v[224:225], v[84:85], v[44:45] neg_lo:[0,0,1] neg_hi:[0,0,1]
	v_mov_b32_dpp v207, v47 row_shr:1 row_mask:0xf bank_mask:0xf bound_ctrl:1
	v_pk_add_f32 v[44:45], v[48:49], v[44:45]
	v_pk_mul_f32 v[48:49], v[224:225], v[86:87]
	v_mov_b32_dpp v206, v46 row_shr:1 row_mask:0xf bank_mask:0xf bound_ctrl:1
	v_pk_fma_f32 v[48:49], v[226:227], v[84:85], v[48:49]
	v_mov_b32_dpp v204, v50 row_shr:1 row_mask:0xf bank_mask:0xf bound_ctrl:1
	v_pk_add_f32 v[48:49], v[82:83], v[48:49]
	v_mov_b32_e32 v82, v220
	v_mov_b32_e32 v83, v222
	v_mov_b32_dpp v205, v51 row_shr:1 row_mask:0xf bank_mask:0xf bound_ctrl:1
	v_pk_mul_f32 v[84:85], v[82:83], v[206:207]
	v_mov_b32_e32 v86, v221
	v_mov_b32_e32 v87, v223
	v_pk_fma_f32 v[84:85], v[86:87], v[204:205], v[84:85]
	v_pk_mul_f32 v[88:89], v[220:221], v[220:221]
	v_pk_add_f32 v[46:47], v[84:85], v[46:47]
	v_pk_mul_f32 v[84:85], v[222:223], v[222:223]
	v_mov_b32_e32 v208, v88
	v_mov_b32_e32 v209, v84
	v_mov_b32_e32 v84, v89
	v_pk_add_f32 v[88:89], v[82:83], v[82:83]
	v_pk_add_f32 v[84:85], v[208:209], v[84:85] neg_lo:[0,1] neg_hi:[0,1]
	v_pk_mul_f32 v[88:89], v[86:87], v[88:89]
	v_pk_mul_f32 v[86:87], v[86:87], v[206:207]
	v_mov_b32_dpp v208, v46 row_shr:2 row_mask:0xf bank_mask:0xf bound_ctrl:1
	v_pk_fma_f32 v[82:83], v[82:83], v[204:205], v[86:87] neg_lo:[0,0,1] neg_hi:[0,0,1]
	v_mov_b32_dpp v209, v47 row_shr:2 row_mask:0xf bank_mask:0xf bound_ctrl:1
	v_pk_add_f32 v[50:51], v[82:83], v[50:51]
	v_pk_mul_f32 v[210:211], v[84:85], v[208:209]
	v_pk_mul_f32 v[212:213], v[88:89], v[88:89]
	v_mov_b32_dpp v82, v50 row_shr:2 row_mask:0xf bank_mask:0xf bound_ctrl:1
	v_mov_b32_dpp v83, v51 row_shr:2 row_mask:0xf bank_mask:0xf bound_ctrl:1
	v_pk_mul_f32 v[86:87], v[88:89], v[208:209]
	v_pk_fma_f32 v[212:213], v[84:85], v[84:85], v[212:213] neg_lo:[0,0,1] neg_hi:[0,0,1]
	v_pk_add_f32 v[214:215], v[84:85], v[84:85]
	v_pk_fma_f32 v[84:85], v[84:85], v[82:83], v[86:87] neg_lo:[0,0,1] neg_hi:[0,0,1]
	v_pk_fma_f32 v[82:83], v[88:89], v[82:83], v[210:211]
	v_pk_mul_f32 v[214:215], v[88:89], v[214:215]
	v_pk_add_f32 v[46:47], v[46:47], v[82:83]
	v_pk_add_f32 v[50:51], v[50:51], v[84:85]
	v_pk_add_f32 v[218:219], v[212:213], v[212:213]
	v_mov_b32_dpp v84, v46 row_shr:4 row_mask:0xf bank_mask:0xf bound_ctrl:1
	v_mov_b32_dpp v85, v47 row_shr:4 row_mask:0xf bank_mask:0xf bound_ctrl:1
	v_mov_b32_dpp v82, v50 row_shr:4 row_mask:0xf bank_mask:0xf bound_ctrl:1
	v_mov_b32_dpp v83, v51 row_shr:4 row_mask:0xf bank_mask:0xf bound_ctrl:1
	v_pk_mul_f32 v[86:87], v[214:215], v[84:85]
	v_pk_mul_f32 v[84:85], v[212:213], v[84:85]
	v_pk_fma_f32 v[86:87], v[212:213], v[82:83], v[86:87] neg_lo:[0,0,1] neg_hi:[0,0,1]
	v_pk_fma_f32 v[82:83], v[214:215], v[82:83], v[84:85]
	v_pk_mul_f32 v[216:217], v[214:215], v[214:215]
	v_pk_add_f32 v[82:83], v[46:47], v[82:83]
	v_pk_mul_f32 v[218:219], v[214:215], v[218:219]
	v_pk_add_f32 v[50:51], v[50:51], v[86:87]
	v_mov_b32_dpp v86, v82 row_shr:8 row_mask:0xf bank_mask:0xf bound_ctrl:1
	v_mov_b32_dpp v87, v83 row_shr:8 row_mask:0xf bank_mask:0xf bound_ctrl:1
	v_pk_fma_f32 v[216:217], v[212:213], v[212:213], v[216:217] neg_lo:[0,0,1] neg_hi:[0,0,1]
	v_mov_b32_dpp v84, v50 row_shr:8 row_mask:0xf bank_mask:0xf bound_ctrl:1
	v_mov_b32_dpp v85, v51 row_shr:8 row_mask:0xf bank_mask:0xf bound_ctrl:1
	v_pk_mul_f32 v[46:47], v[218:219], v[86:87]
	v_mov_b32_dpp v1, v44 row_ror:1 row_mask:0xf bank_mask:0xf bound_ctrl:1
	v_pk_fma_f32 v[46:47], v[216:217], v[84:85], v[46:47] neg_lo:[0,0,1] neg_hi:[0,0,1]
	v_cndmask_b32_e64 v1, v1, v3, s[10:11]
	v_pk_add_f32 v[46:47], v[50:51], v[46:47]
	v_pk_mul_f32 v[50:51], v[216:217], v[86:87]
	v_mov_b32_dpp v3, v45 row_ror:1 row_mask:0xf bank_mask:0xf bound_ctrl:1
	v_pk_fma_f32 v[50:51], v[218:219], v[84:85], v[50:51]
	v_cndmask_b32_e64 v3, v3, v79, s[10:11]
	v_pk_add_f32 v[50:51], v[82:83], v[50:51]
	v_mov_b32_dpp v82, v48 row_ror:1 row_mask:0xf bank_mask:0xf bound_ctrl:1
	v_cndmask_b32_e64 v2, v82, v2, s[10:11]
	v_mov_b32_dpp v79, v46 row_ror:1 row_mask:0xf bank_mask:0xf bound_ctrl:1
	v_mov_b32_dpp v82, v49 row_ror:1 row_mask:0xf bank_mask:0xf bound_ctrl:1
	v_cndmask_b32_e64 v78, v82, v78, s[10:11]
	v_mov_b32_dpp v83, v51 row_ror:1 row_mask:0xf bank_mask:0xf bound_ctrl:1
	v_mov_b32_dpp v82, v50 row_ror:1 row_mask:0xf bank_mask:0xf bound_ctrl:1
	v_cndmask_b32_e64 v84, v82, v90, s[10:11]
	v_cndmask_b32_e64 v79, v79, v91, s[10:11]
	v_mov_b32_dpp v82, v47 row_ror:1 row_mask:0xf bank_mask:0xf bound_ctrl:1
	v_cndmask_b32_e64 v85, v82, v201, s[10:11]
	v_cndmask_b32_e64 v86, v83, v200, s[10:11]
	v_cvt_pk_bf16_f32 v82, v1, v3
	v_cvt_pk_bf16_f32 v83, v79, v85
	v_cvt_pk_bf16_f32 v78, v2, v78
	v_cvt_pk_bf16_f32 v79, v84, v86
	global_load_dwordx4 v[84:87], v[140:141], off
	ds_read_b128 v[88:91], v105 offset:32768
	ds_read_b128 v[204:207], v105 offset:33792
	ds_read_b128 v[208:211], v105 offset:34816
	v_add_u32_e32 v2, s26, v159
	s_waitcnt lgkmcnt(2)
	v_mfma_f32_16x16x32_bf16 v[88:91], v[88:91], v[56:59], 0
	s_waitcnt lgkmcnt(1)
	v_mfma_f32_16x16x32_bf16 v[88:91], v[204:207], v[52:55], v[88:91]
	ds_read_b128 v[204:207], v105 offset:35840
	s_waitcnt lgkmcnt(1)
	v_mfma_f32_16x16x32_bf16 v[88:91], v[208:211], v[64:67], v[88:91]
	ds_read_b128 v[208:211], v164
	s_waitcnt lgkmcnt(1)
	v_mfma_f32_16x16x32_bf16 v[88:91], v[204:207], v[60:63], v[88:91]
	ds_read_b128 v[204:207], v165
	s_waitcnt lgkmcnt(1)
	v_mfma_f32_16x16x32_bf16 v[88:91], v[208:211], v[72:75], v[88:91]
	ds_read_b128 v[208:211], v166
	s_waitcnt lgkmcnt(1)
	v_mfma_f32_16x16x32_bf16 v[88:91], v[204:207], v[80:83], v[88:91]
	ds_read_b128 v[204:207], v167
	s_waitcnt lgkmcnt(1)
	v_mfma_f32_16x16x32_bf16 v[88:91], v[208:211], v[68:71], v[88:91]
	s_waitcnt lgkmcnt(0)
	v_mfma_f32_16x16x32_bf16 v[88:91], v[204:207], v[76:79], v[88:91]
	s_and_saveexec_b64 s[26:27], s[24:25]
	s_cbranch_execz .LBB0_648
; __device__ __forceinline__ unsigned cvt_pk_bf16(float lo, float hi) { unsigned r; asm("v_cvt_pk_bf16_f32 %0, %1, %2" : "=v"(r) : "v"(lo), "v"(hi)); return r; }
; __device__ __forceinline__ float bf_lo(unsigned w) { return __uint_as_float(w << 16); }
; __device__ __forceinline__ float bf_hi(unsigned w) { return __uint_as_float(w & 0xffff0000u); }
; __device__ __forceinline__ float gelu_tanh(float x) {
;     const float t = x * x, u = x * (-2.3022082f - 0.10294324f * t); return x * __builtin_amdgcn_rcpf(1.f + __builtin_amdgcn_exp2f(u)); }
; template <bool PASS2>
; __device__ __forceinline__ void ssm_phase(const Params& p, const Frame& F0) {
;     ...
;                     if (j < nsub) {
;                         const size_t off = (size_t)(row0 + 8 * j + t) * DSSM + g * 16 + 4 * gq;
;                         const u32x2 uu = uw[t];
;                         const float z0 = gelu_tanh(y[0] + dv[0] * bf_lo(uu.x)), z1 = gelu_tanh(y[1] + dv[1] * bf_hi(uu.x)), z2 = gelu_tanh(y[2] + dv[2] * bf_lo(uu.y)), z3 = gelu_tanh(y[3] + dv[3] * bf_hi(uu.y));
;                         *(u32x2*)(Zb + off) = (u32x2){cvt_pk_bf16(z0, z1), cvt_pk_bf16(z2, z3)};
	v_lshlrev_b32_e32 v1, 16, v156
	s_waitcnt vmcnt(0)
	s_nop 3
	v_fma_f32 v1, v84, v1, v88
	v_mul_f32_e32 v3, v1, v1
	v_fmamk_f32 v3, v3, 0xbdd2d3e8, v93
	v_mul_f32_e32 v3, v1, v3
	v_exp_f32_e32 v88, v3
	v_and_b32_e32 v3, 0xffff0000, v156
	v_lshlrev_b32_e32 v199, 16, v157
	v_and_b32_e32 v157, 0xffff0000, v157
	v_fma_f32 v89, v85, v3, v89
	v_fma_f32 v90, v86, v199, v90
	v_fmac_f32_e32 v91, v87, v157
	v_mul_f32_e32 v3, v89, v89
	v_mul_f32_e32 v199, v90, v90
	v_mul_f32_e32 v157, v91, v91
	v_fmamk_f32 v3, v3, 0xbdd2d3e8, v93
	v_fmamk_f32 v199, v199, 0xbdd2d3e8, v93
	v_fmamk_f32 v157, v157, 0xbdd2d3e8, v93
	v_mul_f32_e32 v3, v89, v3
	v_mul_f32_e32 v199, v90, v199
	v_mul_f32_e32 v157, v91, v157
	v_exp_f32_e32 v156, v3
	v_exp_f32_e32 v199, v199
	v_exp_f32_e32 v157, v157
	v_add_f32_e32 v88, 1.0, v88
	v_add_f32_e32 v156, 1.0, v156
	v_add_f32_e32 v199, 1.0, v199
	v_add_f32_e32 v157, 1.0, v157
	v_rcp_f32_e32 v88, v88
	v_rcp_f32_e32 v156, v156
	v_rcp_f32_e32 v199, v199
	v_rcp_f32_e32 v157, v157
	v_ashrrev_i32_e32 v3, 31, v2
	v_mul_f32_e32 v1, v1, v88
	v_mul_f32_e32 v88, v89, v156
	v_mul_f32_e32 v89, v90, v199
	v_mul_f32_e32 v90, v91, v157
	v_cvt_pk_bf16_f32 v89, v89, v90
	v_lshlrev_b64 v[90:91], 10, v[2:3]
	v_lshl_add_u64 v[90:91], v[134:135], 0, v[90:91]
	v_cvt_pk_bf16_f32 v88, v1, v88
	global_store_dwordx2 v[90:91], v[88:89], off
